# attention output stores widened: half-wave permlane32 swaps then 4 dwordx4 stores per lane instead of 8 dwordx2 (on top of blocked hidden layout)
# baseline (speedup 1.0000x reference)
.LBB0_19:
	s_andn2_b64 vcc, exec, s[6:7]
	s_cbranch_vccnz .LBB0_73
	s_cmp_eq_u32 s47, 12
	s_mov_b64 s[10:11], -1
	s_cbranch_scc0 .LBB0_73
	s_waitcnt lgkmcnt(0)
	s_abs_i32 s0, s3
	v_cvt_f32_u32_e32 v0, s0
	s_sub_i32 s6, 0, s0
	s_add_i32 s1, s3, 0xfff
	s_xor_b32 s4, s1, s3
	v_rcp_iflag_f32_e32 v0, v0
	s_abs_i32 s1, s1
	v_writelane_b32 v254, s96, 40
	s_ashr_i32 s4, s4, 31
	v_mul_f32_e32 v0, 0x4f7ffffe, v0
	v_cvt_u32_f32_e32 v0, v0
	v_writelane_b32 v254, s97, 41
	v_writelane_b32 v254, s98, 42
	v_writelane_b32 v254, s76, 43
	v_readfirstlane_b32 s7, v0
	s_mul_i32 s6, s6, s7
	s_mul_hi_u32 s6, s7, s6
	s_add_i32 s7, s7, s6
	s_mul_hi_u32 s6, s1, s7
	s_mul_i32 s7, s6, s0
	s_sub_i32 s1, s1, s7
	s_add_i32 s8, s6, 1
	s_sub_i32 s7, s1, s0
	s_cmp_ge_u32 s1, s0
	s_cselect_b32 s6, s8, s6
	v_writelane_b32 v254, s77, 44
	s_cselect_b32 s1, s7, s1
	s_add_i32 s7, s6, 1
	v_writelane_b32 v254, s75, 45
	s_cmp_ge_u32 s1, s0
	v_writelane_b32 v254, s94, 46
	s_cselect_b32 s0, s7, s6
	s_xor_b32 s0, s0, s4
	v_writelane_b32 v254, s95, 47
	s_sub_i32 s44, s0, s4
	v_readlane_b32 s0, v254, 15
	s_mul_i32 s0, s44, s0
	s_min_i32 s0, s0, 0x1000
	s_mul_i32 s45, s44, s2
	v_writelane_b32 v254, s0, 48
	s_cmp_ge_i32 s45, s0
	v_readfirstlane_b32 s0, v237
	s_cbranch_scc1 .LBB0_72
	s_add_u32 s6, s78, 0xd000000
	s_addc_u32 s7, s79, 0
	s_add_u32 s90, s78, 0x2b000000
	s_addc_u32 s91, s79, 0
	s_add_u32 s92, s78, 0x33000000
	v_writelane_b32 v254, s6, 49
	s_addc_u32 s93, s79, 0
	v_lshrrev_b32_e32 v3, 3, v236
	v_writelane_b32 v254, s7, 50
	s_add_u32 s6, s78, 0x15000000
	s_addc_u32 s7, s79, 0
	s_ashr_i32 s33, s0, 6
	s_andn2_b32 s0, s0, 63
	s_or_b32 s4, s0, 8
	v_or_b32_e32 v126, s4, v3
	s_lshl_b32 s50, s4, 7
	s_or_b32 s4, s0, 16
	v_or_b32_e32 v127, s4, v3
	s_lshl_b32 s52, s4, 7
	s_or_b32 s4, s0, 24
	v_or_b32_e32 v128, s4, v3
	s_lshl_b32 s53, s4, 7
	s_or_b32 s4, s0, 32
	v_or_b32_e32 v129, s4, v3
	s_lshl_b32 s68, s4, 7
	s_or_b32 s4, s0, 40
	v_or_b32_e32 v125, s0, v3
	s_lshl_b32 s46, s0, 7
	v_or_b32_e32 v130, s4, v3
	s_lshl_b32 s69, s4, 7
	s_or_b32 s4, s0, 48
	s_or_b32 s0, s0, 56
	v_or_b32_e32 v132, s0, v3
	v_or_b32_e32 v131, s4, v3
	v_lshrrev_b32_e32 v3, 1, v132
	v_xor_b32_e32 v3, v3, v237
	s_lshl_b32 s1, s33, 3
	v_lshlrev_b32_e32 v3, 3, v3
	v_and_b32_e32 v18, 56, v3
	s_lshl_b32 s76, s0, 7
	v_bitop3_b32 v3, s1, v236, 8 bitop3:0x6c
	s_or_b32 s0, s1, 1
	v_lshlrev_b32_e32 v133, 3, v3
	v_bitop3_b32 v3, s0, v236, 9 bitop3:0x6c
	s_or_b32 s60, s1, 2
	v_lshlrev_b32_e32 v134, 3, v3
	v_bitop3_b32 v3, s60, v236, 10 bitop3:0x6c
	s_or_b32 s64, s1, 3
	v_lshlrev_b32_e32 v135, 3, v3
	v_bitop3_b32 v3, s64, v236, 11 bitop3:0x6c
	s_or_b32 s54, s1, 4
	v_lshlrev_b32_e32 v0, 1, v237
	v_lshrrev_b32_e32 v2, 1, v237
	v_lshlrev_b32_e32 v136, 3, v3
	v_bitop3_b32 v3, s54, v236, 12 bitop3:0x6c
	s_or_b32 s63, s1, 5
	v_and_b32_e32 v1, 19, v237
	v_and_b32_e32 v0, 8, v0
	v_and_b32_e32 v2, 4, v2
	v_lshlrev_b32_e32 v137, 3, v3
	v_bitop3_b32 v3, s63, v236, 13 bitop3:0x6c
	s_or_b32 s67, s1, 6
	v_or3_b32 v96, v0, v1, v2
	s_lshl_b32 s75, s4, 7
	v_lshlrev_b32_e32 v138, 3, v3
	v_bitop3_b32 v3, s67, v236, 14 bitop3:0x6c
	s_or_b32 s4, s1, 7
	v_lshrrev_b32_e32 v95, 5, v236
	v_lshrrev_b32_e32 v5, 1, v96
	v_lshlrev_b32_e32 v139, 3, v3
	v_bitop3_b32 v3, s4, v236, 15 bitop3:0x6c
	v_lshlrev_b32_e32 v140, 3, v3
	v_bitop3_b32 v3, v5, v95, 7 bitop3:0x6c
	v_lshlrev_b32_e32 v141, 4, v3
	v_or_b32_e32 v3, 2, v95
	v_bitop3_b32 v3, v5, v3, 7 bitop3:0x6c
	v_lshlrev_b32_e32 v142, 4, v3
	v_or_b32_e32 v3, 4, v95
	v_bitop3_b32 v3, v5, v3, 7 bitop3:0x6c
	v_lshlrev_b32_e32 v143, 4, v3
	v_or_b32_e32 v3, 6, v95
	v_bitop3_b32 v3, v5, v3, 7 bitop3:0x6c
	v_lshlrev_b32_e32 v0, 3, v95
	v_lshlrev_b32_e32 v144, 4, v3
	v_lshlrev_b32_e32 v3, 8, v237
	v_and_b32_e32 v94, 31, v237
	v_or_b32_e32 v2, 1, v0
	v_lshrrev_b32_e32 v7, 1, v127
	v_and_b32_e32 v3, 0x400, v3
	v_lshlrev_b32_e32 v5, 6, v237
	v_cmp_lt_u32_e64 s[10:11], v2, v94
	v_or_b32_e32 v2, 2, v0
	v_xor_b32_e32 v7, v7, v237
	v_lshl_or_b32 v3, s33, 12, v3
	v_and_b32_e32 v5, 0x200, v5
	v_lshlrev_b32_e32 v1, 7, v1
	v_cmp_lt_u32_e64 s[12:13], v2, v94
	v_or_b32_e32 v2, 3, v0
	v_lshlrev_b32_e32 v7, 3, v7
	v_or3_b32 v1, v3, v5, v1
	v_cmp_lt_u32_e64 s[14:15], v2, v94
	v_or_b32_e32 v2, 4, v0
	v_and_b32_e32 v8, 56, v7
	v_lshrrev_b32_e32 v7, 1, v128
	v_add_u32_e32 v145, 0, v1
	v_and_b32_e32 v1, 32, v237
	v_writelane_b32 v254, s6, 51
	v_cmp_lt_u32_e64 s[16:17], v2, v94
	v_or_b32_e32 v2, 5, v0
	v_xor_b32_e32 v7, v7, v237
	v_lshrrev_b32_e32 v1, 1, v1
	v_writelane_b32 v254, s7, 52
	v_cmp_lt_u32_e64 s[18:19], v2, v94
	v_or_b32_e32 v2, 6, v0
	v_lshlrev_b32_e32 v7, 3, v7
	s_lshl_b32 s48, s33, 5
	v_lshl_or_b32 v48, v96, 11, v1
	v_cmp_lt_u32_e64 s[20:21], v2, v94
	v_or_b32_e32 v2, 7, v0
	v_and_b32_e32 v10, 56, v7
	v_lshrrev_b32_e32 v7, 1, v129
	v_writelane_b32 v254, s48, 53
	v_lshl_add_u64 v[20:21], s[78:79], 0, v[48:49]
	s_mov_b64 s[48:49], 0x2b000040
	v_cmp_lt_u32_e64 s[22:23], v2, v94
	v_or_b32_e32 v2, 16, v0
	v_xor_b32_e32 v7, v7, v237
	v_lshl_add_u64 v[98:99], v[20:21], 0, s[48:49]
	s_add_i32 s48, s33, -1
	v_cmp_lt_u32_e64 s[24:25], v2, v94
	v_or_b32_e32 v2, 17, v0
	v_lshlrev_b32_e32 v7, 3, v7
	v_writelane_b32 v254, s48, 54
	v_cmp_lt_u32_e64 s[26:27], v2, v94
	v_or_b32_e32 v2, 18, v0
	v_and_b32_e32 v12, 56, v7
	v_lshrrev_b32_e32 v7, 1, v130
	v_readlane_b32 s48, v254, 17
	v_cmp_lt_u32_e64 s[28:29], v2, v94
	v_or_b32_e32 v2, 19, v0
	v_xor_b32_e32 v7, v7, v237
	s_mul_i32 s56, s44, s2
	s_mul_i32 s55, s48, s44
	s_add_i32 s44, s46, 0
	v_cmp_lt_u32_e64 s[30:31], v2, v94
	v_or_b32_e32 v2, 20, v0
	v_lshlrev_b32_e32 v7, 3, v7
	v_writelane_b32 v254, s44, 55
	s_add_i32 s44, s50, 0
	v_cmp_lt_u32_e64 s[34:35], v2, v94
	v_or_b32_e32 v2, 21, v0
	v_lshrrev_b32_e32 v4, 4, v236
	v_lshrrev_b32_e32 v6, 1, v126
	v_and_b32_e32 v14, 56, v7
	v_lshrrev_b32_e32 v7, 1, v131
	v_writelane_b32 v254, s44, 56
	s_add_i32 s44, s52, 0
	v_cmp_lt_u32_e64 s[36:37], v2, v94
	v_or_b32_e32 v2, 22, v0
	v_xor_b32_e32 v4, v4, v237
	v_xor_b32_e32 v6, v6, v237
	v_xor_b32_e32 v7, v7, v237
	v_writelane_b32 v254, s44, 57
	s_add_i32 s44, s53, 0
	v_cmp_lt_u32_e64 s[38:39], v2, v94
	v_or_b32_e32 v2, 23, v0
	v_lshlrev_b32_e32 v4, 3, v4
	v_lshlrev_b32_e32 v6, 3, v6
	v_lshlrev_b32_e32 v7, 3, v7
	v_writelane_b32 v254, s44, 58
	s_add_i32 s44, s68, 0
	v_cmp_lt_u32_e64 s[40:41], v2, v94
	v_lshlrev_b32_e32 v2, 2, v95
	v_and_b32_e32 v4, 56, v4
	v_and_b32_e32 v6, 56, v6
	v_and_b32_e32 v16, 56, v7
	s_lshl_b32 s77, s33, 13
	s_lshl_b32 s84, s0, 10
	s_lshl_b32 s85, s60, 10
	s_lshl_b32 s88, s64, 10
	s_lshl_b32 s89, s54, 10
	s_lshl_b32 s94, s63, 10
	s_lshl_b32 s95, s67, 10
	s_lshl_b32 s96, s4, 10
	v_writelane_b32 v254, s44, 59
	s_add_i32 s44, s69, 0
	v_lshl_add_u32 v97, v94, 10, s62
	v_and_b32_e32 v124, 15, v237
	v_cmp_gt_u32_e64 s[6:7], 32, v236
	v_cmp_lt_u32_e64 s[8:9], v0, v94
	v_lshlrev_b32_e32 v100, 1, v4
	v_mov_b32_e32 v101, v49
	v_lshlrev_b32_e32 v102, 1, v6
	v_mov_b32_e32 v103, v49
	v_lshlrev_b32_e32 v104, 1, v8
	v_mov_b32_e32 v105, v49
	v_lshlrev_b32_e32 v106, 1, v10
	v_mov_b32_e32 v107, v49
	v_lshlrev_b32_e32 v108, 1, v12
	v_mov_b32_e32 v109, v49
	v_lshlrev_b32_e32 v110, 1, v14
	v_mov_b32_e32 v111, v49
	v_writelane_b32 v254, s44, 60
	v_lshlrev_b32_e32 v112, 1, v16
	v_mov_b32_e32 v113, v49
	s_add_i32 s75, s75, 0
	v_lshlrev_b32_e32 v114, 1, v18
	v_mov_b32_e32 v115, v49
	s_add_i32 s76, s76, 0
	v_lshlrev_b32_e32 v48, 1, v0
	v_lshlrev_b32_e32 v116, 2, v2
	s_add_i32 s77, s62, s77
	s_add_i32 s84, s62, s84
	s_add_i32 s85, s62, s85
	s_add_i32 s88, s62, s88
	s_add_i32 s89, s62, s89
	s_add_i32 s94, s62, s94
	s_add_i32 s95, s62, s95
	s_add_i32 s44, s62, s96
	s_branch .LBB0_49

.LBB0_48:
	v_readlane_b32 s48, v254, 51
	v_lshlrev_b64 v[32:33], 10, v[118:119]
	v_readlane_b32 s49, v254, 52
	s_mov_b32 s97, s51
	v_mov_b32_e32 v117, v49
	v_lshl_add_u64 v[32:33], v[32:33], 1, s[48:49]
	v_lshl_add_u64 v[32:33], v[32:33], 0, s[96:97]
	v_lshl_add_u64 v[32:33], v[32:33], 0, v[116:117]
	v_cvt_pk_bf16_f32 v36, v0, v1
	v_cvt_pk_bf16_f32 v37, v2, v3
	v_cvt_pk_bf16_f32 v38, v4, v5
	v_cvt_pk_bf16_f32 v39, v6, v7
	v_cvt_pk_bf16_f32 v40, v16, v17
	v_cvt_pk_bf16_f32 v41, v18, v19
	v_cvt_pk_bf16_f32 v42, v20, v21
	v_cvt_pk_bf16_f32 v43, v22, v23
	s_nop 1
	v_permlane32_swap_b32_e32 v36, v38
	v_permlane32_swap_b32_e32 v37, v39
	v_permlane32_swap_b32_e32 v40, v42
	v_permlane32_swap_b32_e32 v41, v43
	s_add_i32 s45, s45, 1
	s_add_i32 s56, s56, 1
	global_store_dwordx4 v[32:33], v[36:39], off
	global_store_dwordx4 v[32:33], v[40:43], off offset:64
	v_cvt_pk_bf16_f32 v44, v8, v9
	v_cvt_pk_bf16_f32 v45, v10, v11
	v_cvt_pk_bf16_f32 v46, v12, v13
	v_cvt_pk_bf16_f32 v47, v14, v15
	v_cvt_pk_bf16_f32 v24, v24, v25
	v_cvt_pk_bf16_f32 v25, v26, v27
	v_cvt_pk_bf16_f32 v26, v28, v29
	v_cvt_pk_bf16_f32 v27, v30, v31
	s_add_i32 s55, s55, 2
	v_readlane_b32 s46, v254, 48
	s_nop 1
	v_permlane32_swap_b32_e32 v44, v46
	v_permlane32_swap_b32_e32 v45, v47
	v_permlane32_swap_b32_e32 v24, v26
	v_permlane32_swap_b32_e32 v25, v27
	s_cmp_lt_i32 s45, s46
	global_store_dwordx4 v[32:33], v[44:47], off offset:32
	global_store_dwordx4 v[32:33], v[24:27], off offset:96
	s_nop 1
	s_cbranch_scc0 .LBB0_72
